# GEMM K-loop heads aligned to 64 bytes (on top of P5 epilogue rewrite etc.)
# baseline (speedup 1.0000x reference)
.LBB0_121:
	s_ashr_i32 s27, s26, 31
	s_lshl_b64 s[28:29], s[26:27], 19
	s_add_u32 s28, s78, s28
	s_addc_u32 s29, s79, s29
	s_and_b64 s[30:31], s[40:41], exec
	s_cselect_b32 s1, s29, s37
	s_cselect_b32 s27, s28, s36
	s_ashr_i32 s25, s24, 31
	s_lshl_b64 s[30:31], s[24:25], 19
	s_add_u32 s30, s4, s30
	s_addc_u32 s31, s5, s31
	s_and_b64 s[40:41], s[40:41], exec
	s_cselect_b32 s25, s31, s39
	s_cselect_b32 s35, s30, s38
	s_add_u32 s36, s36, 0x40080
	s_addc_u32 s37, s37, 0
	s_add_u32 s57, s38, 0x100
	v_mov_b32_e32 v2, 0
	s_addc_u32 s58, s39, 0
	s_mov_b32 s59, -2
	v_mov_b32_e32 v3, 0
	v_mov_b64_e32 v[4:5], 0
	v_mov_b64_e32 v[6:7], 0
	v_mov_b64_e32 v[8:9], 0
	v_mov_b64_e32 v[10:11], 0
	v_mov_b64_e32 v[12:13], 0
	v_mov_b64_e32 v[14:15], 0
	v_mov_b64_e32 v[16:17], 0
	v_mov_b64_e32 v[18:19], 0
	v_mov_b64_e32 v[20:21], 0
	v_mov_b64_e32 v[22:23], 0
	v_mov_b64_e32 v[24:25], 0
	v_mov_b64_e32 v[26:27], 0
	v_mov_b64_e32 v[28:29], 0
	v_mov_b64_e32 v[30:31], 0
	v_mov_b64_e32 v[32:33], 0
	v_mov_b64_e32 v[34:35], 0
	v_mov_b64_e32 v[36:37], 0
	v_mov_b64_e32 v[38:39], 0
	v_mov_b64_e32 v[40:41], 0
	v_mov_b64_e32 v[42:43], 0
	v_mov_b64_e32 v[44:45], 0
	v_mov_b64_e32 v[46:47], 0
	v_mov_b64_e32 v[48:49], 0
	v_mov_b64_e32 v[50:51], 0
	v_mov_b64_e32 v[52:53], 0
	v_mov_b64_e32 v[54:55], 0
	v_mov_b64_e32 v[56:57], 0
	v_mov_b64_e32 v[58:59], 0
	v_mov_b64_e32 v[60:61], 0
	v_mov_b64_e32 v[62:63], 0
	v_mov_b64_e32 v[64:65], 0
	v_mov_b64_e32 v[66:67], 0
	v_mov_b64_e32 v[68:69], 0
	v_mov_b64_e32 v[70:71], 0
	v_mov_b64_e32 v[72:73], 0
	v_mov_b64_e32 v[74:75], 0
	v_mov_b64_e32 v[76:77], 0
	v_mov_b64_e32 v[78:79], 0
	v_mov_b64_e32 v[80:81], 0
	v_mov_b64_e32 v[82:83], 0
	v_mov_b64_e32 v[84:85], 0
	v_mov_b64_e32 v[86:87], 0
	v_mov_b64_e32 v[88:89], 0
	v_mov_b64_e32 v[90:91], 0
	v_mov_b64_e32 v[92:93], 0
	v_mov_b64_e32 v[94:95], 0
	v_mov_b64_e32 v[96:97], 0
	v_mov_b64_e32 v[98:99], 0
	v_mov_b64_e32 v[100:101], 0
	v_mov_b64_e32 v[102:103], 0
	v_mov_b64_e32 v[104:105], 0
	v_mov_b64_e32 v[106:107], 0
	v_mov_b64_e32 v[108:109], 0
	v_mov_b64_e32 v[110:111], 0
	v_mov_b64_e32 v[112:113], 0
	v_mov_b64_e32 v[114:115], 0
	v_mov_b64_e32 v[116:117], 0
	v_mov_b64_e32 v[118:119], 0
	v_mov_b64_e32 v[120:121], 0
	v_mov_b64_e32 v[122:123], 0
	v_mov_b64_e32 v[124:125], 0
	v_mov_b64_e32 v[126:127], 0
	v_mov_b64_e32 v[128:129], 0
	.p2align	6

.LBB0_580:
	s_ashr_i32 s11, s10, 31
	s_lshl_b64 s[12:13], s[10:11], 19
	s_add_u32 s12, s96, s12
	s_addc_u32 s13, s97, s13
	s_and_b64 s[14:15], s[24:25], exec
	s_cselect_b32 s11, s13, s19
	s_cselect_b32 s42, s12, s18
	s_ashr_i32 s9, s8, 31
	s_lshl_b64 s[14:15], s[8:9], 19
	s_add_u32 s14, s56, s14
	s_addc_u32 s15, s57, s15
	v_lshl_add_u32 v2, s16, 9, v187
	s_and_b64 s[24:25], s[24:25], exec
	v_ashrrev_i32_e32 v3, 31, v2
	s_cselect_b32 s9, s15, s23
	s_cselect_b32 s43, s14, s22
	v_lshl_add_u64 v[160:161], v[2:3], 1, s[92:93]
	s_add_u32 s44, s22, 0x100
	v_mov_b32_e32 v2, 0
	v_lshl_add_u32 v158, s20, 8, v184
	v_lshl_add_u64 v[174:175], s[18:19], 0, v[170:171]
	v_lshl_add_u64 v[176:177], s[18:19], 0, v[172:173]
	s_addc_u32 s45, s23, 0
	s_mov_b32 s46, -2
	s_mov_b64 s[20:21], 0
	v_mov_b32_e32 v3, 0
	v_mov_b64_e32 v[4:5], 0
	v_mov_b64_e32 v[6:7], 0
	v_mov_b64_e32 v[8:9], 0
	v_mov_b64_e32 v[10:11], 0
	v_mov_b64_e32 v[12:13], 0
	v_mov_b64_e32 v[14:15], 0
	v_mov_b64_e32 v[16:17], 0
	v_mov_b64_e32 v[18:19], 0
	v_mov_b64_e32 v[20:21], 0
	v_mov_b64_e32 v[22:23], 0
	v_mov_b64_e32 v[24:25], 0
	v_mov_b64_e32 v[26:27], 0
	v_mov_b64_e32 v[28:29], 0
	v_mov_b64_e32 v[30:31], 0
	v_mov_b64_e32 v[32:33], 0
	v_mov_b64_e32 v[34:35], 0
	v_mov_b64_e32 v[36:37], 0
	v_mov_b64_e32 v[38:39], 0
	v_mov_b64_e32 v[40:41], 0
	v_mov_b64_e32 v[42:43], 0
	v_mov_b64_e32 v[44:45], 0
	v_mov_b64_e32 v[46:47], 0
	v_mov_b64_e32 v[48:49], 0
	v_mov_b64_e32 v[50:51], 0
	v_mov_b64_e32 v[52:53], 0
	v_mov_b64_e32 v[54:55], 0
	v_mov_b64_e32 v[56:57], 0
	v_mov_b64_e32 v[58:59], 0
	v_mov_b64_e32 v[60:61], 0
	v_mov_b64_e32 v[62:63], 0
	v_mov_b64_e32 v[64:65], 0
	v_mov_b64_e32 v[66:67], 0
	v_mov_b64_e32 v[68:69], 0
	v_mov_b64_e32 v[70:71], 0
	v_mov_b64_e32 v[72:73], 0
	v_mov_b64_e32 v[74:75], 0
	v_mov_b64_e32 v[76:77], 0
	v_mov_b64_e32 v[78:79], 0
	v_mov_b64_e32 v[80:81], 0
	v_mov_b64_e32 v[82:83], 0
	v_mov_b64_e32 v[84:85], 0
	v_mov_b64_e32 v[86:87], 0
	v_mov_b64_e32 v[88:89], 0
	v_mov_b64_e32 v[90:91], 0
	v_mov_b64_e32 v[92:93], 0
	v_mov_b64_e32 v[94:95], 0
	v_mov_b64_e32 v[96:97], 0
	v_mov_b64_e32 v[98:99], 0
	v_mov_b64_e32 v[100:101], 0
	v_mov_b64_e32 v[102:103], 0
	v_mov_b64_e32 v[104:105], 0
	v_mov_b64_e32 v[106:107], 0
	v_mov_b64_e32 v[108:109], 0
	v_mov_b64_e32 v[110:111], 0
	v_mov_b64_e32 v[112:113], 0
	v_mov_b64_e32 v[114:115], 0
	v_mov_b64_e32 v[116:117], 0
	v_mov_b64_e32 v[118:119], 0
	v_mov_b64_e32 v[120:121], 0
	v_mov_b64_e32 v[122:123], 0
	v_mov_b64_e32 v[124:125], 0
	v_mov_b64_e32 v[126:127], 0
	v_mov_b64_e32 v[128:129], 0
	s_branch .LBB0_582
	.p2align	6

.LBB0_670:
	s_ashr_i32 s21, s20, 31
	s_lshl_b64 s[22:23], s[20:21], 19
	s_add_u32 s22, s78, s22
	s_addc_u32 s23, s79, s23
	s_and_b64 s[24:25], s[26:27], exec
	s_cselect_b32 s5, s23, s9
	s_cselect_b32 s7, s22, s8
	s_ashr_i32 s19, s18, 31
	s_lshl_b64 s[24:25], s[18:19], 19
	s_add_u32 s24, s66, s24
	s_addc_u32 s25, s67, s25
	s_and_b64 s[26:27], s[26:27], exec
	s_cselect_b32 s19, s25, s11
	s_cselect_b32 s21, s24, s10
	s_add_u32 s8, s8, 0x40080
	s_addc_u32 s9, s9, 0
	s_add_u32 s56, s10, 0x100
	v_mov_b32_e32 v2, 0
	s_addc_u32 s57, s11, 0
	s_mov_b32 s58, -2
	s_waitcnt lgkmcnt(0)
	v_mov_b32_e32 v3, 0
	v_mov_b64_e32 v[4:5], 0
	v_mov_b64_e32 v[6:7], 0
	v_mov_b64_e32 v[8:9], 0
	v_mov_b64_e32 v[10:11], 0
	v_mov_b64_e32 v[12:13], 0
	v_mov_b64_e32 v[14:15], 0
	v_mov_b64_e32 v[16:17], 0
	v_mov_b64_e32 v[18:19], 0
	v_mov_b64_e32 v[20:21], 0
	v_mov_b64_e32 v[22:23], 0
	v_mov_b64_e32 v[24:25], 0
	v_mov_b64_e32 v[26:27], 0
	v_mov_b64_e32 v[28:29], 0
	v_mov_b64_e32 v[30:31], 0
	v_mov_b64_e32 v[32:33], 0
	v_mov_b64_e32 v[34:35], 0
	v_mov_b64_e32 v[36:37], 0
	v_mov_b64_e32 v[38:39], 0
	v_mov_b64_e32 v[40:41], 0
	v_mov_b64_e32 v[42:43], 0
	v_mov_b64_e32 v[44:45], 0
	v_mov_b64_e32 v[46:47], 0
	v_mov_b64_e32 v[48:49], 0
	v_mov_b64_e32 v[50:51], 0
	v_mov_b64_e32 v[52:53], 0
	v_mov_b64_e32 v[54:55], 0
	v_mov_b64_e32 v[56:57], 0
	v_mov_b64_e32 v[58:59], 0
	v_mov_b64_e32 v[60:61], 0
	v_mov_b64_e32 v[62:63], 0
	v_mov_b64_e32 v[64:65], 0
	v_mov_b64_e32 v[66:67], 0
	v_mov_b64_e32 v[68:69], 0
	v_mov_b64_e32 v[70:71], 0
	v_mov_b64_e32 v[72:73], 0
	v_mov_b64_e32 v[74:75], 0
	v_mov_b64_e32 v[76:77], 0
	v_mov_b64_e32 v[78:79], 0
	v_mov_b64_e32 v[80:81], 0
	v_mov_b64_e32 v[82:83], 0
	v_mov_b64_e32 v[84:85], 0
	v_mov_b64_e32 v[86:87], 0
	v_mov_b64_e32 v[88:89], 0
	v_mov_b64_e32 v[90:91], 0
	v_mov_b64_e32 v[92:93], 0
	v_mov_b64_e32 v[94:95], 0
	v_mov_b64_e32 v[96:97], 0
	v_mov_b64_e32 v[98:99], 0
	v_mov_b64_e32 v[100:101], 0
	v_mov_b64_e32 v[102:103], 0
	v_mov_b64_e32 v[104:105], 0
	v_mov_b64_e32 v[106:107], 0
	v_mov_b64_e32 v[108:109], 0
	v_mov_b64_e32 v[110:111], 0
	v_mov_b64_e32 v[112:113], 0
	v_mov_b64_e32 v[114:115], 0
	v_mov_b64_e32 v[116:117], 0
	v_mov_b64_e32 v[118:119], 0
	v_mov_b64_e32 v[120:121], 0
	v_mov_b64_e32 v[122:123], 0
	v_mov_b64_e32 v[124:125], 0
	v_mov_b64_e32 v[126:127], 0
	v_mov_b64_e32 v[128:129], 0
	.p2align	6

.LBB0_840:
	s_ashr_i32 s11, s10, 31
	s_lshl_b64 s[12:13], s[10:11], 19
	s_add_u32 s12, s96, s12
	s_addc_u32 s13, s97, s13
	s_and_b64 s[14:15], s[24:25], exec
	s_cselect_b32 s11, s13, s21
	s_cselect_b32 s41, s12, s20
	s_ashr_i32 s9, s8, 31
	s_lshl_b64 s[14:15], s[8:9], 19
	s_add_u32 s14, s50, s14
	s_addc_u32 s15, s51, s15
	s_and_b64 s[24:25], s[24:25], exec
	s_cselect_b32 s9, s15, s23
	s_cselect_b32 s42, s14, s22
	s_add_u32 s20, s20, 0x40080
	s_addc_u32 s21, s21, 0
	s_add_u32 s43, s22, 0x100
	v_mov_b32_e32 v2, 0
	s_addc_u32 s44, s23, 0
	s_mov_b32 s45, -2
	v_mov_b32_e32 v3, 0
	v_mov_b64_e32 v[4:5], 0
	v_mov_b64_e32 v[6:7], 0
	v_mov_b64_e32 v[8:9], 0
	v_mov_b64_e32 v[10:11], 0
	v_mov_b64_e32 v[12:13], 0
	v_mov_b64_e32 v[14:15], 0
	v_mov_b64_e32 v[16:17], 0
	v_mov_b64_e32 v[18:19], 0
	v_mov_b64_e32 v[20:21], 0
	v_mov_b64_e32 v[22:23], 0
	v_mov_b64_e32 v[24:25], 0
	v_mov_b64_e32 v[26:27], 0
	v_mov_b64_e32 v[28:29], 0
	v_mov_b64_e32 v[30:31], 0
	v_mov_b64_e32 v[32:33], 0
	v_mov_b64_e32 v[34:35], 0
	v_mov_b64_e32 v[36:37], 0
	v_mov_b64_e32 v[38:39], 0
	v_mov_b64_e32 v[40:41], 0
	v_mov_b64_e32 v[42:43], 0
	v_mov_b64_e32 v[44:45], 0
	v_mov_b64_e32 v[46:47], 0
	v_mov_b64_e32 v[48:49], 0
	v_mov_b64_e32 v[50:51], 0
	v_mov_b64_e32 v[52:53], 0
	v_mov_b64_e32 v[54:55], 0
	v_mov_b64_e32 v[56:57], 0
	v_mov_b64_e32 v[58:59], 0
	v_mov_b64_e32 v[60:61], 0
	v_mov_b64_e32 v[62:63], 0
	v_mov_b64_e32 v[64:65], 0
	v_mov_b64_e32 v[66:67], 0
	v_mov_b64_e32 v[68:69], 0
	v_mov_b64_e32 v[70:71], 0
	v_mov_b64_e32 v[72:73], 0
	v_mov_b64_e32 v[74:75], 0
	v_mov_b64_e32 v[76:77], 0
	v_mov_b64_e32 v[78:79], 0
	v_mov_b64_e32 v[80:81], 0
	v_mov_b64_e32 v[82:83], 0
	v_mov_b64_e32 v[84:85], 0
	v_mov_b64_e32 v[86:87], 0
	v_mov_b64_e32 v[88:89], 0
	v_mov_b64_e32 v[90:91], 0
	v_mov_b64_e32 v[92:93], 0
	v_mov_b64_e32 v[94:95], 0
	v_mov_b64_e32 v[96:97], 0
	v_mov_b64_e32 v[98:99], 0
	v_mov_b64_e32 v[100:101], 0
	v_mov_b64_e32 v[102:103], 0
	v_mov_b64_e32 v[104:105], 0
	v_mov_b64_e32 v[106:107], 0
	v_mov_b64_e32 v[108:109], 0
	v_mov_b64_e32 v[110:111], 0
	v_mov_b64_e32 v[112:113], 0
	v_mov_b64_e32 v[114:115], 0
	v_mov_b64_e32 v[116:117], 0
	v_mov_b64_e32 v[118:119], 0
	v_mov_b64_e32 v[120:121], 0
	v_mov_b64_e32 v[122:123], 0
	v_mov_b64_e32 v[124:125], 0
	v_mov_b64_e32 v[126:127], 0
	v_mov_b64_e32 v[128:129], 0
	.p2align	6

.LBB0_927:
	s_add_u32 s10, s10, 0xb0080
	s_addc_u32 s11, s11, 0
	s_add_u32 s44, s12, 0x100
	v_mov_b32_e32 v2, 0
	s_addc_u32 s45, s13, 0
	s_mov_b32 s46, -2
	v_mov_b32_e32 v3, 0
	v_mov_b64_e32 v[4:5], 0
	v_mov_b64_e32 v[6:7], 0
	v_mov_b64_e32 v[8:9], 0
	v_mov_b64_e32 v[10:11], 0
	v_mov_b64_e32 v[12:13], 0
	v_mov_b64_e32 v[14:15], 0
	v_mov_b64_e32 v[16:17], 0
	v_mov_b64_e32 v[18:19], 0
	v_mov_b64_e32 v[20:21], 0
	v_mov_b64_e32 v[22:23], 0
	v_mov_b64_e32 v[24:25], 0
	v_mov_b64_e32 v[26:27], 0
	v_mov_b64_e32 v[28:29], 0
	v_mov_b64_e32 v[30:31], 0
	v_mov_b64_e32 v[32:33], 0
	v_mov_b64_e32 v[34:35], 0
	v_mov_b64_e32 v[36:37], 0
	v_mov_b64_e32 v[38:39], 0
	v_mov_b64_e32 v[40:41], 0
	v_mov_b64_e32 v[42:43], 0
	v_mov_b64_e32 v[44:45], 0
	v_mov_b64_e32 v[46:47], 0
	v_mov_b64_e32 v[48:49], 0
	v_mov_b64_e32 v[50:51], 0
	v_mov_b64_e32 v[52:53], 0
	v_mov_b64_e32 v[54:55], 0
	v_mov_b64_e32 v[56:57], 0
	v_mov_b64_e32 v[58:59], 0
	v_mov_b64_e32 v[60:61], 0
	v_mov_b64_e32 v[62:63], 0
	v_mov_b64_e32 v[64:65], 0
	v_mov_b64_e32 v[66:67], 0
	v_mov_b64_e32 v[68:69], 0
	v_mov_b64_e32 v[70:71], 0
	v_mov_b64_e32 v[72:73], 0
	v_mov_b64_e32 v[74:75], 0
	v_mov_b64_e32 v[76:77], 0
	v_mov_b64_e32 v[78:79], 0
	v_mov_b64_e32 v[80:81], 0
	v_mov_b64_e32 v[82:83], 0
	v_mov_b64_e32 v[84:85], 0
	v_mov_b64_e32 v[86:87], 0
	v_mov_b64_e32 v[88:89], 0
	v_mov_b64_e32 v[90:91], 0
	v_mov_b64_e32 v[92:93], 0
	v_mov_b64_e32 v[94:95], 0
	v_mov_b64_e32 v[96:97], 0
	v_mov_b64_e32 v[98:99], 0
	v_mov_b64_e32 v[100:101], 0
	v_mov_b64_e32 v[102:103], 0
	v_mov_b64_e32 v[104:105], 0
	v_mov_b64_e32 v[106:107], 0
	v_mov_b64_e32 v[108:109], 0
	v_mov_b64_e32 v[110:111], 0
	v_mov_b64_e32 v[112:113], 0
	v_mov_b64_e32 v[114:115], 0
	v_mov_b64_e32 v[116:117], 0
	v_mov_b64_e32 v[118:119], 0
	v_mov_b64_e32 v[120:121], 0
	v_mov_b64_e32 v[122:123], 0
	v_mov_b64_e32 v[124:125], 0
	v_mov_b64_e32 v[126:127], 0
	v_mov_b64_e32 v[128:129], 0
	.p2align	6
